# v13 + GEMM DMA stagger variant: waves 4-7 issue next-stage DMA after one MFMA group of the next step
# baseline (speedup 1.0000x reference)
; #define MFMA16(a, b, c) __builtin_amdgcn_mfma_f32_16x16x32_bf16((a), (b), (c), 0, 0, 0)
;   DI unsigned koff(int k) const { return (unsigned)((k >> 6) * EIN + (k & 63)); }
; DI void dma16(const void* g, unsigned char* l) { __builtin_amdgcn_global_load_lds((const unsigned*)g, (lds_u32_t*)(unsigned)(size_t)l, 16, 0, 0); }
; template <class AF, class EF>
; DI void gemm_run(unsigned char* lds, int wv, const AF& af, const bf16_t* __restrict__ Bt, int ldb, int M, int N, int K, const EF& ef, int blk_off) {
;     ...
;     for (int kt = 0; kt < nk; ++kt) {
;       unsigned char* cur = sBase + (kt & 1) * GST;
;       if (kt + 1 < nk) {
;         unsigned char* nxt = sBase + ((kt + 1) & 1) * GST;
;         const int k0 = (kt + 1) << 6;
; #pragma unroll
;         for (int i = 0; i < 4; ++i) {
;           dma16(Ab + aoff[i] + af.koff(k0 + cch), nxt + 32768 + (i * 512 + tid) * 16);
;           dma16(Bt + boff[i] + (unsigned)k0, nxt + (i * 512 + tid) * 16);
;         }
;       }
; #pragma unroll
;       for (int ks = 0; ks < 2; ++ks) {
;         bf16x8 wf[4], xf[8];
; #pragma unroll
;         for (int i = 0; i < 4; ++i) wf[i] = *(const bf16x8*)(cur + (wn * 64 + i * 16 + l15) * 128 + (((ks * 4 + q4) ^ swz) * 16));
; #pragma unroll
;         for (int j = 0; j < 8; ++j) xf[j] = *(const bf16x8*)(cur + 32768 + (wm * 128 + j * 16 + l15) * 128 + (((ks * 4 + q4) ^ swz) * 16));
; #pragma unroll
;         for (int i = 0; i < 4; ++i)
; #pragma unroll
;           for (int j = 0; j < 8; ++j) acc[i][j] = MFMA16(wf[i], xf[j], acc[i][j]);
;       }
.Lmyg120_loop:
	s_waitcnt lgkmcnt(7)
	v_mfma_f32_16x16x32_bf16 v[126:129], v[130:133], v[180:183], v[126:129]
	ds_read_b128 v[226:229], v212 offset:10240
	s_waitcnt lgkmcnt(7)
	v_mfma_f32_16x16x32_bf16 v[118:121], v[130:133], v[184:187], v[118:121]
	s_waitcnt lgkmcnt(6)
	v_mfma_f32_16x16x32_bf16 v[110:113], v[130:133], v[188:191], v[110:113]
	s_waitcnt lgkmcnt(5)
	v_mfma_f32_16x16x32_bf16 v[102:105], v[130:133], v[192:195], v[102:105]
	s_waitcnt lgkmcnt(4)
	v_mfma_f32_16x16x32_bf16 v[94:97], v[130:133], v[196:199], v[94:97]
	s_waitcnt lgkmcnt(3)
	v_mfma_f32_16x16x32_bf16 v[86:89], v[130:133], v[200:203], v[86:89]
	s_waitcnt lgkmcnt(2)
	v_mfma_f32_16x16x32_bf16 v[78:81], v[130:133], v[204:207], v[78:81]
	s_waitcnt lgkmcnt(1)
	v_mfma_f32_16x16x32_bf16 v[70:73], v[130:133], v[208:211], v[70:73]
	s_bitcmp1_b32 s101, 0
	s_cbranch_scc0 .Lmyg120_noB
	s_andn2_b32 s101, s101, 1
	s_setprio 3
	s_and_b32 s15, s14, 0x10000
	s_add_i32 s15, s15, 0
	s_add_i32 s16, s15, 0x2000
	s_add_i32 s15, s15, 0xa000
	v_add_u32_e32 v224, s15, v136
	v_lshl_add_u64 v[222:223], v[160:161], 0, s[4:5]
	v_readfirstlane_b32 s17, v224
	v_add_u32_e32 v224, s16, v136
	s_mov_b32 m0, s17
	v_readfirstlane_b32 s17, v224
	v_add_u32_e32 v224, s15, v138
	global_load_lds_dwordx4 v[222:223], off
	v_lshl_add_u64 v[222:223], v[152:153], 0, s[4:5]
	s_mov_b32 m0, s17
	v_readfirstlane_b32 s17, v224
	v_add_u32_e32 v224, s16, v138
	global_load_lds_dwordx4 v[222:223], off
	v_lshl_add_u64 v[222:223], v[158:159], 0, s[4:5]
	s_mov_b32 m0, s17
	v_readfirstlane_b32 s17, v224
	v_add_u32_e32 v224, s15, v140
	global_load_lds_dwordx4 v[222:223], off
	v_lshl_add_u64 v[222:223], v[150:151], 0, s[4:5]
	s_mov_b32 m0, s17
	v_readfirstlane_b32 s17, v224
	v_add_u32_e32 v224, s16, v140
	global_load_lds_dwordx4 v[222:223], off
	v_lshl_add_u64 v[222:223], v[156:157], 0, s[4:5]
	s_mov_b32 m0, s17
	v_readfirstlane_b32 s17, v224
	v_add_u32_e32 v224, s15, v142
	global_load_lds_dwordx4 v[222:223], off
	v_lshl_add_u64 v[222:223], v[148:149], 0, s[4:5]
	s_mov_b32 m0, s17
	v_readfirstlane_b32 s15, v224
	v_add_u32_e32 v224, s16, v142
	global_load_lds_dwordx4 v[222:223], off
	v_lshl_add_u64 v[222:223], v[154:155], 0, s[4:5]
	s_mov_b32 m0, s15
	v_readfirstlane_b32 s15, v224
	global_load_lds_dwordx4 v[222:223], off
	v_lshl_add_u64 v[222:223], v[146:147], 0, s[4:5]
	s_mov_b32 m0, s15
	s_nop 0
	global_load_lds_dwordx4 v[222:223], off
	s_setprio 0
; #define MFMA16(a, b, c) __builtin_amdgcn_mfma_f32_16x16x32_bf16((a), (b), (c), 0, 0, 0)
; DI void vm_wait0() { asm volatile("s_waitcnt vmcnt(0)" ::: "memory"); }
;   DI unsigned koff(int k) const { return (unsigned)((k >> 6) * EIN + (k & 63)); }
; DI void dma16(const void* g, unsigned char* l) { __builtin_amdgcn_global_load_lds((const unsigned*)g, (lds_u32_t*)(unsigned)(size_t)l, 16, 0, 0); }
; template <class AF, class EF>
; DI void gemm_run(unsigned char* lds, int wv, const AF& af, const bf16_t* __restrict__ Bt, int ldb, int M, int N, int K, const EF& ef, int blk_off) {
;     ...
;       if (kt + 1 < nk) {
;         unsigned char* nxt = sBase + ((kt + 1) & 1) * GST;
;         const int k0 = (kt + 1) << 6;
; #pragma unroll
;         for (int i = 0; i < 4; ++i) {
;           dma16(Ab + aoff[i] + af.koff(k0 + cch), nxt + 32768 + (i * 512 + tid) * 16);
;           dma16(Bt + boff[i] + (unsigned)k0, nxt + (i * 512 + tid) * 16);
;         }
;     ...
; #pragma unroll
;       for (int ks = 0; ks < 2; ++ks) {
;         bf16x8 wf[4], xf[8];
; #pragma unroll
;         for (int i = 0; i < 4; ++i) wf[i] = *(const bf16x8*)(cur + (wn * 64 + i * 16 + l15) * 128 + (((ks * 4 + q4) ^ swz) * 16));
; #pragma unroll
;         for (int j = 0; j < 8; ++j) xf[j] = *(const bf16x8*)(cur + 32768 + (wm * 128 + j * 16 + l15) * 128 + (((ks * 4 + q4) ^ swz) * 16));
; #pragma unroll
;         for (int i = 0; i < 4; ++i)
; #pragma unroll
;           for (int j = 0; j < 8; ++j) acc[i][j] = MFMA16(wf[i], xf[j], acc[i][j]);
;       }
;       vm_wait0();
;       __syncthreads();
;     }
.Lmyg120_noB:
	s_waitcnt lgkmcnt(0)
	v_mfma_f32_16x16x32_bf16 v[122:125], v[226:229], v[180:183], v[122:125]
	ds_read_b128 v[130:133], v212 offset:12288
	v_mfma_f32_16x16x32_bf16 v[114:117], v[226:229], v[184:187], v[114:117]
	v_mfma_f32_16x16x32_bf16 v[106:109], v[226:229], v[188:191], v[106:109]
	v_mfma_f32_16x16x32_bf16 v[98:101], v[226:229], v[192:195], v[98:101]
	v_mfma_f32_16x16x32_bf16 v[90:93], v[226:229], v[196:199], v[90:93]
	v_mfma_f32_16x16x32_bf16 v[82:85], v[226:229], v[200:203], v[82:85]
	v_mfma_f32_16x16x32_bf16 v[74:77], v[226:229], v[204:207], v[74:77]
	v_mfma_f32_16x16x32_bf16 v[66:69], v[226:229], v[208:211], v[66:69]
	s_waitcnt lgkmcnt(0)
	v_mfma_f32_16x16x32_bf16 v[58:61], v[130:133], v[180:183], v[58:61]
	ds_read_b128 v[226:229], v212 offset:14336
	v_mfma_f32_16x16x32_bf16 v[50:53], v[130:133], v[184:187], v[50:53]
	v_add_u32_e32 v0, s100, v179
	v_mfma_f32_16x16x32_bf16 v[42:45], v[130:133], v[188:191], v[42:45]
	v_add3_u32 v212, v0, v176, v177
	v_mfma_f32_16x16x32_bf16 v[34:37], v[130:133], v[192:195], v[34:37]
	v_add3_u32 v0, v0, v178, v177
	v_mfma_f32_16x16x32_bf16 v[26:29], v[130:133], v[196:199], v[26:29]
	v_mfma_f32_16x16x32_bf16 v[18:21], v[130:133], v[200:203], v[18:21]
	v_mfma_f32_16x16x32_bf16 v[6:9], v[130:133], v[204:207], v[6:9]
	v_mfma_f32_16x16x32_bf16 v[2:5], v[130:133], v[208:211], v[2:5]
	s_waitcnt lgkmcnt(0)
	v_mfma_f32_16x16x32_bf16 v[62:65], v[226:229], v[180:183], v[62:65]
	ds_read_b128 v[130:133], v212 offset:8192
	ds_read_b128 v[180:183], v0 offset:40960
	v_mfma_f32_16x16x32_bf16 v[54:57], v[226:229], v[184:187], v[54:57]
	ds_read_b128 v[184:187], v0 offset:43008
	v_mfma_f32_16x16x32_bf16 v[46:49], v[226:229], v[188:191], v[46:49]
	ds_read_b128 v[188:191], v0 offset:45056
	v_mfma_f32_16x16x32_bf16 v[38:41], v[226:229], v[192:195], v[38:41]
	ds_read_b128 v[192:195], v0 offset:47104
	v_mfma_f32_16x16x32_bf16 v[30:33], v[226:229], v[196:199], v[30:33]
	ds_read_b128 v[196:199], v0 offset:49152
	v_mfma_f32_16x16x32_bf16 v[22:25], v[226:229], v[200:203], v[22:25]
	ds_read_b128 v[200:203], v0 offset:51200
	v_mfma_f32_16x16x32_bf16 v[14:17], v[226:229], v[204:207], v[14:17]
	ds_read_b128 v[204:207], v0 offset:53248
	v_mfma_f32_16x16x32_bf16 v[10:13], v[226:229], v[208:211], v[10:13]
	ds_read_b128 v[208:211], v0 offset:55296
	s_waitcnt lgkmcnt(7)
	v_mfma_f32_16x16x32_bf16 v[126:129], v[130:133], v[180:183], v[126:129]
	ds_read_b128 v[226:229], v212 offset:10240
	s_waitcnt lgkmcnt(7)
	v_mfma_f32_16x16x32_bf16 v[118:121], v[130:133], v[184:187], v[118:121]
	s_waitcnt lgkmcnt(6)
	v_mfma_f32_16x16x32_bf16 v[110:113], v[130:133], v[188:191], v[110:113]
	s_waitcnt lgkmcnt(5)
	v_mfma_f32_16x16x32_bf16 v[102:105], v[130:133], v[192:195], v[102:105]
	s_waitcnt lgkmcnt(4)
	v_mfma_f32_16x16x32_bf16 v[94:97], v[130:133], v[196:199], v[94:97]
	s_waitcnt lgkmcnt(3)
	v_mfma_f32_16x16x32_bf16 v[86:89], v[130:133], v[200:203], v[86:89]
	s_waitcnt lgkmcnt(2)
	v_mfma_f32_16x16x32_bf16 v[78:81], v[130:133], v[204:207], v[78:81]
	s_waitcnt lgkmcnt(1)
	v_mfma_f32_16x16x32_bf16 v[70:73], v[130:133], v[208:211], v[70:73]
	s_waitcnt lgkmcnt(0)
	v_mfma_f32_16x16x32_bf16 v[122:125], v[226:229], v[180:183], v[122:125]
	ds_read_b128 v[130:133], v212 offset:12288
	v_mfma_f32_16x16x32_bf16 v[114:117], v[226:229], v[184:187], v[114:117]
	v_mfma_f32_16x16x32_bf16 v[106:109], v[226:229], v[188:191], v[106:109]
	v_mfma_f32_16x16x32_bf16 v[98:101], v[226:229], v[192:195], v[98:101]
	v_mfma_f32_16x16x32_bf16 v[90:93], v[226:229], v[196:199], v[90:93]
	v_mfma_f32_16x16x32_bf16 v[82:85], v[226:229], v[200:203], v[82:85]
	v_mfma_f32_16x16x32_bf16 v[74:77], v[226:229], v[204:207], v[74:77]
	v_mfma_f32_16x16x32_bf16 v[66:69], v[226:229], v[208:211], v[66:69]
	s_waitcnt lgkmcnt(0)
	v_mfma_f32_16x16x32_bf16 v[58:61], v[130:133], v[180:183], v[58:61]
	ds_read_b128 v[226:229], v212 offset:14336
	v_mfma_f32_16x16x32_bf16 v[50:53], v[130:133], v[184:187], v[50:53]
	v_mfma_f32_16x16x32_bf16 v[42:45], v[130:133], v[188:191], v[42:45]
	v_mfma_f32_16x16x32_bf16 v[34:37], v[130:133], v[192:195], v[34:37]
	v_mfma_f32_16x16x32_bf16 v[26:29], v[130:133], v[196:199], v[26:29]
	v_mfma_f32_16x16x32_bf16 v[18:21], v[130:133], v[200:203], v[18:21]
	v_mfma_f32_16x16x32_bf16 v[6:9], v[130:133], v[204:207], v[6:9]
	v_mfma_f32_16x16x32_bf16 v[2:5], v[130:133], v[208:211], v[2:5]
	s_waitcnt vmcnt(0) lgkmcnt(0)
	s_barrier
	s_add_u32 s4, s4, 0x80
	s_addc_u32 s5, s5, 0
	s_add_i32 s14, s14, 0x10000
	s_cmpk_eq_i32 s4, 0x800
	s_cbranch_scc1 .Lmyg120_tail
	s_add_i32 s100, s14, 0xffff0000
	s_and_b32 s100, s100, 0x10000
	v_add_u32_e32 v0, s100, v175
	v_add3_u32 v212, v0, v176, v177
	v_add3_u32 v0, v0, v178, v177
	s_cmpk_eq_i32 s4, 0x780
	s_cbranch_scc1 .Lmyg120_nodma
	s_bitcmp1_b32 s101, 1
	s_cbranch_scc1 .Lmyg120_defer
	s_setprio 3
	s_and_b32 s15, s14, 0x10000
	s_add_i32 s15, s15, 0
	s_add_i32 s16, s15, 0x2000
	s_add_i32 s15, s15, 0xa000
	v_add_u32_e32 v224, s15, v136
	v_lshl_add_u64 v[222:223], v[160:161], 0, s[4:5]
	v_readfirstlane_b32 s17, v224
	v_add_u32_e32 v224, s16, v136
	s_mov_b32 m0, s17
	v_readfirstlane_b32 s17, v224
	v_add_u32_e32 v224, s15, v138
	global_load_lds_dwordx4 v[222:223], off
	v_lshl_add_u64 v[222:223], v[152:153], 0, s[4:5]
	s_mov_b32 m0, s17
	v_readfirstlane_b32 s17, v224
	v_add_u32_e32 v224, s16, v138
	global_load_lds_dwordx4 v[222:223], off
	v_lshl_add_u64 v[222:223], v[158:159], 0, s[4:5]
	s_mov_b32 m0, s17
	v_readfirstlane_b32 s17, v224
	v_add_u32_e32 v224, s15, v140
	global_load_lds_dwordx4 v[222:223], off
	v_lshl_add_u64 v[222:223], v[150:151], 0, s[4:5]
	s_mov_b32 m0, s17
	v_readfirstlane_b32 s17, v224
	v_add_u32_e32 v224, s16, v140
	global_load_lds_dwordx4 v[222:223], off
	v_lshl_add_u64 v[222:223], v[156:157], 0, s[4:5]
	s_mov_b32 m0, s17
	v_readfirstlane_b32 s17, v224
	v_add_u32_e32 v224, s15, v142
	global_load_lds_dwordx4 v[222:223], off
	v_lshl_add_u64 v[222:223], v[148:149], 0, s[4:5]
	s_mov_b32 m0, s17
	v_readfirstlane_b32 s15, v224
	v_add_u32_e32 v224, s16, v142
	global_load_lds_dwordx4 v[222:223], off
	v_lshl_add_u64 v[222:223], v[154:155], 0, s[4:5]
	s_mov_b32 m0, s15
	v_readfirstlane_b32 s15, v224
	global_load_lds_dwordx4 v[222:223], off
	v_lshl_add_u64 v[222:223], v[146:147], 0, s[4:5]
	s_mov_b32 m0, s15
	s_nop 0
	global_load_lds_dwordx4 v[222:223], off
	s_setprio 0
	s_branch .Lmyg120_nodma

; #define MFMA16(a, b, c) __builtin_amdgcn_mfma_f32_16x16x32_bf16((a), (b), (c), 0, 0, 0)
;   DI unsigned koff(int k) const { return (unsigned)((k >> 6) * EIN + (k & 63)); }
; DI void dma16(const void* g, unsigned char* l) { __builtin_amdgcn_global_load_lds((const unsigned*)g, (lds_u32_t*)(unsigned)(size_t)l, 16, 0, 0); }
; template <class AF, class EF>
; DI void gemm_run(unsigned char* lds, int wv, const AF& af, const bf16_t* __restrict__ Bt, int ldb, int M, int N, int K, const EF& ef, int blk_off) {
;     ...
;     for (int kt = 0; kt < nk; ++kt) {
;       unsigned char* cur = sBase + (kt & 1) * GST;
;       if (kt + 1 < nk) {
;         unsigned char* nxt = sBase + ((kt + 1) & 1) * GST;
;         const int k0 = (kt + 1) << 6;
; #pragma unroll
;         for (int i = 0; i < 4; ++i) {
;           dma16(Ab + aoff[i] + af.koff(k0 + cch), nxt + 32768 + (i * 512 + tid) * 16);
;           dma16(Bt + boff[i] + (unsigned)k0, nxt + (i * 512 + tid) * 16);
;         }
;       }
; #pragma unroll
;       for (int ks = 0; ks < 2; ++ks) {
;         bf16x8 wf[4], xf[8];
; #pragma unroll
;         for (int i = 0; i < 4; ++i) wf[i] = *(const bf16x8*)(cur + (wn * 64 + i * 16 + l15) * 128 + (((ks * 4 + q4) ^ swz) * 16));
; #pragma unroll
;         for (int j = 0; j < 8; ++j) xf[j] = *(const bf16x8*)(cur + 32768 + (wm * 128 + j * 16 + l15) * 128 + (((ks * 4 + q4) ^ swz) * 16));
; #pragma unroll
;         for (int i = 0; i < 4; ++i)
; #pragma unroll
;           for (int j = 0; j < 8; ++j) acc[i][j] = MFMA16(wf[i], xf[j], acc[i][j]);
;       }
.Lmyg261_loop:
	s_waitcnt lgkmcnt(7)
	v_mfma_f32_16x16x32_bf16 v[126:129], v[130:133], v[180:183], v[126:129]
	ds_read_b128 v[226:229], v212 offset:10240
	s_waitcnt lgkmcnt(7)
	v_mfma_f32_16x16x32_bf16 v[118:121], v[130:133], v[184:187], v[118:121]
	s_waitcnt lgkmcnt(6)
	v_mfma_f32_16x16x32_bf16 v[110:113], v[130:133], v[188:191], v[110:113]
	s_waitcnt lgkmcnt(5)
	v_mfma_f32_16x16x32_bf16 v[102:105], v[130:133], v[192:195], v[102:105]
	s_waitcnt lgkmcnt(4)
	v_mfma_f32_16x16x32_bf16 v[94:97], v[130:133], v[196:199], v[94:97]
	s_waitcnt lgkmcnt(3)
	v_mfma_f32_16x16x32_bf16 v[86:89], v[130:133], v[200:203], v[86:89]
	s_waitcnt lgkmcnt(2)
	v_mfma_f32_16x16x32_bf16 v[78:81], v[130:133], v[204:207], v[78:81]
	s_waitcnt lgkmcnt(1)
	v_mfma_f32_16x16x32_bf16 v[70:73], v[130:133], v[208:211], v[70:73]
	s_bitcmp1_b32 s101, 0
	s_cbranch_scc0 .Lmyg261_noB
	s_andn2_b32 s101, s101, 1
	s_setprio 3
	s_and_b32 s17, s16, 0x10000
	s_add_i32 s17, s17, 0
	s_add_i32 s18, s17, 0x2000
	s_add_i32 s17, s17, 0xa000
	v_add_u32_e32 v224, s17, v136
	v_lshl_add_u64 v[222:223], v[160:161], 0, s[4:5]
	v_readfirstlane_b32 s19, v224
	v_add_u32_e32 v224, s18, v136
	s_mov_b32 m0, s19
	v_readfirstlane_b32 s19, v224
	v_add_u32_e32 v224, s17, v138
	global_load_lds_dwordx4 v[222:223], off
	v_lshl_add_u64 v[222:223], v[152:153], 0, s[4:5]
	s_mov_b32 m0, s19
	v_readfirstlane_b32 s19, v224
	v_add_u32_e32 v224, s18, v138
	global_load_lds_dwordx4 v[222:223], off
	v_lshl_add_u64 v[222:223], v[158:159], 0, s[4:5]
	s_mov_b32 m0, s19
	v_readfirstlane_b32 s19, v224
	v_add_u32_e32 v224, s17, v140
	global_load_lds_dwordx4 v[222:223], off
	v_lshl_add_u64 v[222:223], v[150:151], 0, s[4:5]
	s_mov_b32 m0, s19
	v_readfirstlane_b32 s19, v224
	v_add_u32_e32 v224, s18, v140
	global_load_lds_dwordx4 v[222:223], off
	v_lshl_add_u64 v[222:223], v[156:157], 0, s[4:5]
	s_mov_b32 m0, s19
	v_readfirstlane_b32 s19, v224
	v_add_u32_e32 v224, s17, v142
	global_load_lds_dwordx4 v[222:223], off
	v_lshl_add_u64 v[222:223], v[148:149], 0, s[4:5]
	s_mov_b32 m0, s19
	v_readfirstlane_b32 s17, v224
	v_add_u32_e32 v224, s18, v142
	global_load_lds_dwordx4 v[222:223], off
	v_lshl_add_u64 v[222:223], v[154:155], 0, s[4:5]
	s_mov_b32 m0, s17
	v_readfirstlane_b32 s17, v224
	global_load_lds_dwordx4 v[222:223], off
	v_lshl_add_u64 v[222:223], v[146:147], 0, s[4:5]
	s_mov_b32 m0, s17
	s_nop 0
	global_load_lds_dwordx4 v[222:223], off
	s_setprio 0
; #define MFMA16(a, b, c) __builtin_amdgcn_mfma_f32_16x16x32_bf16((a), (b), (c), 0, 0, 0)
; DI void vm_wait0() { asm volatile("s_waitcnt vmcnt(0)" ::: "memory"); }
;   DI unsigned koff(int k) const { return (unsigned)((k >> 6) * EIN + (k & 63)); }
; DI void dma16(const void* g, unsigned char* l) { __builtin_amdgcn_global_load_lds((const unsigned*)g, (lds_u32_t*)(unsigned)(size_t)l, 16, 0, 0); }
; template <class AF, class EF>
; DI void gemm_run(unsigned char* lds, int wv, const AF& af, const bf16_t* __restrict__ Bt, int ldb, int M, int N, int K, const EF& ef, int blk_off) {
;     ...
;       if (kt + 1 < nk) {
;         unsigned char* nxt = sBase + ((kt + 1) & 1) * GST;
;         const int k0 = (kt + 1) << 6;
; #pragma unroll
;         for (int i = 0; i < 4; ++i) {
;           dma16(Ab + aoff[i] + af.koff(k0 + cch), nxt + 32768 + (i * 512 + tid) * 16);
;           dma16(Bt + boff[i] + (unsigned)k0, nxt + (i * 512 + tid) * 16);
;         }
;     ...
; #pragma unroll
;       for (int ks = 0; ks < 2; ++ks) {
;         bf16x8 wf[4], xf[8];
; #pragma unroll
;         for (int i = 0; i < 4; ++i) wf[i] = *(const bf16x8*)(cur + (wn * 64 + i * 16 + l15) * 128 + (((ks * 4 + q4) ^ swz) * 16));
; #pragma unroll
;         for (int j = 0; j < 8; ++j) xf[j] = *(const bf16x8*)(cur + 32768 + (wm * 128 + j * 16 + l15) * 128 + (((ks * 4 + q4) ^ swz) * 16));
; #pragma unroll
;         for (int i = 0; i < 4; ++i)
; #pragma unroll
;           for (int j = 0; j < 8; ++j) acc[i][j] = MFMA16(wf[i], xf[j], acc[i][j]);
;       }
;       vm_wait0();
;       __syncthreads();
;     }
.Lmyg261_noB:
	s_waitcnt lgkmcnt(0)
	v_mfma_f32_16x16x32_bf16 v[122:125], v[226:229], v[180:183], v[122:125]
	ds_read_b128 v[130:133], v212 offset:12288
	v_mfma_f32_16x16x32_bf16 v[114:117], v[226:229], v[184:187], v[114:117]
	v_mfma_f32_16x16x32_bf16 v[106:109], v[226:229], v[188:191], v[106:109]
	v_mfma_f32_16x16x32_bf16 v[98:101], v[226:229], v[192:195], v[98:101]
	v_mfma_f32_16x16x32_bf16 v[90:93], v[226:229], v[196:199], v[90:93]
	v_mfma_f32_16x16x32_bf16 v[82:85], v[226:229], v[200:203], v[82:85]
	v_mfma_f32_16x16x32_bf16 v[74:77], v[226:229], v[204:207], v[74:77]
	v_mfma_f32_16x16x32_bf16 v[66:69], v[226:229], v[208:211], v[66:69]
	s_waitcnt lgkmcnt(0)
	v_mfma_f32_16x16x32_bf16 v[62:65], v[130:133], v[180:183], v[62:65]
	ds_read_b128 v[226:229], v212 offset:14336
	v_mfma_f32_16x16x32_bf16 v[54:57], v[130:133], v[184:187], v[54:57]
	v_add_u32_e32 v0, s100, v179
	v_mfma_f32_16x16x32_bf16 v[46:49], v[130:133], v[188:191], v[46:49]
	v_add3_u32 v212, v0, v176, v177
	v_mfma_f32_16x16x32_bf16 v[38:41], v[130:133], v[192:195], v[38:41]
	v_add3_u32 v0, v0, v178, v177
	v_mfma_f32_16x16x32_bf16 v[30:33], v[130:133], v[196:199], v[30:33]
	v_mfma_f32_16x16x32_bf16 v[22:25], v[130:133], v[200:203], v[22:25]
	v_mfma_f32_16x16x32_bf16 v[14:17], v[130:133], v[204:207], v[14:17]
	v_mfma_f32_16x16x32_bf16 v[2:5], v[130:133], v[208:211], v[2:5]
	s_waitcnt lgkmcnt(0)
	v_mfma_f32_16x16x32_bf16 v[58:61], v[226:229], v[180:183], v[58:61]
	ds_read_b128 v[130:133], v212 offset:8192
	ds_read_b128 v[180:183], v0 offset:40960
	v_mfma_f32_16x16x32_bf16 v[50:53], v[226:229], v[184:187], v[50:53]
	ds_read_b128 v[184:187], v0 offset:43008
	v_mfma_f32_16x16x32_bf16 v[42:45], v[226:229], v[188:191], v[42:45]
	ds_read_b128 v[188:191], v0 offset:45056
	v_mfma_f32_16x16x32_bf16 v[34:37], v[226:229], v[192:195], v[34:37]
	ds_read_b128 v[192:195], v0 offset:47104
	v_mfma_f32_16x16x32_bf16 v[26:29], v[226:229], v[196:199], v[26:29]
	ds_read_b128 v[196:199], v0 offset:49152
	v_mfma_f32_16x16x32_bf16 v[18:21], v[226:229], v[200:203], v[18:21]
	ds_read_b128 v[200:203], v0 offset:51200
	v_mfma_f32_16x16x32_bf16 v[10:13], v[226:229], v[204:207], v[10:13]
	ds_read_b128 v[204:207], v0 offset:53248
	v_mfma_f32_16x16x32_bf16 v[6:9], v[226:229], v[208:211], v[6:9]
	ds_read_b128 v[208:211], v0 offset:55296
	s_waitcnt lgkmcnt(7)
	v_mfma_f32_16x16x32_bf16 v[126:129], v[130:133], v[180:183], v[126:129]
	ds_read_b128 v[226:229], v212 offset:10240
	s_waitcnt lgkmcnt(7)
	v_mfma_f32_16x16x32_bf16 v[118:121], v[130:133], v[184:187], v[118:121]
	s_waitcnt lgkmcnt(6)
	v_mfma_f32_16x16x32_bf16 v[110:113], v[130:133], v[188:191], v[110:113]
	s_waitcnt lgkmcnt(5)
	v_mfma_f32_16x16x32_bf16 v[102:105], v[130:133], v[192:195], v[102:105]
	s_waitcnt lgkmcnt(4)
	v_mfma_f32_16x16x32_bf16 v[94:97], v[130:133], v[196:199], v[94:97]
	s_waitcnt lgkmcnt(3)
	v_mfma_f32_16x16x32_bf16 v[86:89], v[130:133], v[200:203], v[86:89]
	s_waitcnt lgkmcnt(2)
	v_mfma_f32_16x16x32_bf16 v[78:81], v[130:133], v[204:207], v[78:81]
	s_waitcnt lgkmcnt(1)
	v_mfma_f32_16x16x32_bf16 v[70:73], v[130:133], v[208:211], v[70:73]
	s_waitcnt lgkmcnt(0)
	v_mfma_f32_16x16x32_bf16 v[122:125], v[226:229], v[180:183], v[122:125]
	ds_read_b128 v[130:133], v212 offset:12288
	v_mfma_f32_16x16x32_bf16 v[114:117], v[226:229], v[184:187], v[114:117]
	v_mfma_f32_16x16x32_bf16 v[106:109], v[226:229], v[188:191], v[106:109]
	v_mfma_f32_16x16x32_bf16 v[98:101], v[226:229], v[192:195], v[98:101]
	v_mfma_f32_16x16x32_bf16 v[90:93], v[226:229], v[196:199], v[90:93]
	v_mfma_f32_16x16x32_bf16 v[82:85], v[226:229], v[200:203], v[82:85]
	v_mfma_f32_16x16x32_bf16 v[74:77], v[226:229], v[204:207], v[74:77]
	v_mfma_f32_16x16x32_bf16 v[66:69], v[226:229], v[208:211], v[66:69]
	s_waitcnt lgkmcnt(0)
	v_mfma_f32_16x16x32_bf16 v[62:65], v[130:133], v[180:183], v[62:65]
	ds_read_b128 v[226:229], v212 offset:14336
	v_mfma_f32_16x16x32_bf16 v[54:57], v[130:133], v[184:187], v[54:57]
	v_mfma_f32_16x16x32_bf16 v[46:49], v[130:133], v[188:191], v[46:49]
	v_mfma_f32_16x16x32_bf16 v[38:41], v[130:133], v[192:195], v[38:41]
	v_mfma_f32_16x16x32_bf16 v[30:33], v[130:133], v[196:199], v[30:33]
	v_mfma_f32_16x16x32_bf16 v[22:25], v[130:133], v[200:203], v[22:25]
	v_mfma_f32_16x16x32_bf16 v[14:17], v[130:133], v[204:207], v[14:17]
	v_mfma_f32_16x16x32_bf16 v[2:5], v[130:133], v[208:211], v[2:5]
	s_waitcnt vmcnt(0) lgkmcnt(0)
	s_barrier
	s_add_u32 s4, s4, 0x80
	s_addc_u32 s5, s5, 0
	s_add_i32 s16, s16, 0x10000
	s_cmpk_eq_i32 s4, 0x800
	s_cbranch_scc1 .Lmyg261_tail
	s_add_i32 s100, s16, 0xffff0000
	s_and_b32 s100, s100, 0x10000
	v_add_u32_e32 v0, s100, v175
	v_add3_u32 v212, v0, v176, v177
	v_add3_u32 v0, v0, v178, v177
	s_cmpk_eq_i32 s4, 0x780
	s_cbranch_scc1 .Lmyg261_nodma
	s_bitcmp1_b32 s101, 1
	s_cbranch_scc1 .Lmyg261_defer
	s_setprio 3
	s_and_b32 s17, s16, 0x10000
	s_add_i32 s17, s17, 0
	s_add_i32 s18, s17, 0x2000
	s_add_i32 s17, s17, 0xa000
	v_add_u32_e32 v224, s17, v136
	v_lshl_add_u64 v[222:223], v[160:161], 0, s[4:5]
	v_readfirstlane_b32 s19, v224
	v_add_u32_e32 v224, s18, v136
	s_mov_b32 m0, s19
	v_readfirstlane_b32 s19, v224
	v_add_u32_e32 v224, s17, v138
	global_load_lds_dwordx4 v[222:223], off
	v_lshl_add_u64 v[222:223], v[152:153], 0, s[4:5]
	s_mov_b32 m0, s19
	v_readfirstlane_b32 s19, v224
	v_add_u32_e32 v224, s18, v138
	global_load_lds_dwordx4 v[222:223], off
	v_lshl_add_u64 v[222:223], v[158:159], 0, s[4:5]
	s_mov_b32 m0, s19
	v_readfirstlane_b32 s19, v224
	v_add_u32_e32 v224, s17, v140
	global_load_lds_dwordx4 v[222:223], off
	v_lshl_add_u64 v[222:223], v[150:151], 0, s[4:5]
	s_mov_b32 m0, s19
	v_readfirstlane_b32 s19, v224
	v_add_u32_e32 v224, s18, v140
	global_load_lds_dwordx4 v[222:223], off
	v_lshl_add_u64 v[222:223], v[156:157], 0, s[4:5]
	s_mov_b32 m0, s19
	v_readfirstlane_b32 s19, v224
	v_add_u32_e32 v224, s17, v142
	global_load_lds_dwordx4 v[222:223], off
	v_lshl_add_u64 v[222:223], v[148:149], 0, s[4:5]
	s_mov_b32 m0, s19
	v_readfirstlane_b32 s17, v224
	v_add_u32_e32 v224, s18, v142
	global_load_lds_dwordx4 v[222:223], off
	v_lshl_add_u64 v[222:223], v[154:155], 0, s[4:5]
	s_mov_b32 m0, s17
	v_readfirstlane_b32 s17, v224
	global_load_lds_dwordx4 v[222:223], off
	v_lshl_add_u64 v[222:223], v[146:147], 0, s[4:5]
	s_mov_b32 m0, s17
	s_nop 0
	global_load_lds_dwordx4 v[222:223], off
	s_setprio 0
	s_branch .Lmyg261_nodma

; #define MFMA16(a, b, c) __builtin_amdgcn_mfma_f32_16x16x32_bf16((a), (b), (c), 0, 0, 0)
;   DI unsigned koff(int k) const { return (unsigned)((k >> 6) * EIN + (k & 63)); }
; DI void dma16(const void* g, unsigned char* l) { __builtin_amdgcn_global_load_lds((const unsigned*)g, (lds_u32_t*)(unsigned)(size_t)l, 16, 0, 0); }
; template <class AF, class EF>
; DI void gemm_run(unsigned char* lds, int wv, const AF& af, const bf16_t* __restrict__ Bt, int ldb, int M, int N, int K, const EF& ef, int blk_off) {
;     ...
;     for (int kt = 0; kt < nk; ++kt) {
;       unsigned char* cur = sBase + (kt & 1) * GST;
;       if (kt + 1 < nk) {
;         unsigned char* nxt = sBase + ((kt + 1) & 1) * GST;
;         const int k0 = (kt + 1) << 6;
; #pragma unroll
;         for (int i = 0; i < 4; ++i) {
;           dma16(Ab + aoff[i] + af.koff(k0 + cch), nxt + 32768 + (i * 512 + tid) * 16);
;           dma16(Bt + boff[i] + (unsigned)k0, nxt + (i * 512 + tid) * 16);
;         }
;       }
; #pragma unroll
;       for (int ks = 0; ks < 2; ++ks) {
;         bf16x8 wf[4], xf[8];
; #pragma unroll
;         for (int i = 0; i < 4; ++i) wf[i] = *(const bf16x8*)(cur + (wn * 64 + i * 16 + l15) * 128 + (((ks * 4 + q4) ^ swz) * 16));
; #pragma unroll
;         for (int j = 0; j < 8; ++j) xf[j] = *(const bf16x8*)(cur + 32768 + (wm * 128 + j * 16 + l15) * 128 + (((ks * 4 + q4) ^ swz) * 16));
; #pragma unroll
;         for (int i = 0; i < 4; ++i)
; #pragma unroll
;           for (int j = 0; j < 8; ++j) acc[i][j] = MFMA16(wf[i], xf[j], acc[i][j]);
;       }
.Lmyg1245_loop:
	s_waitcnt lgkmcnt(7)
	v_mfma_f32_16x16x32_bf16 v[118:121], v[130:133], v[184:187], v[118:121]
	ds_read_b128 v[226:229], v212 offset:10240
	s_waitcnt lgkmcnt(7)
	v_mfma_f32_16x16x32_bf16 v[126:129], v[130:133], v[134:137], v[126:129]
	s_waitcnt lgkmcnt(6)
	v_mfma_f32_16x16x32_bf16 v[110:113], v[130:133], v[188:191], v[110:113]
	s_waitcnt lgkmcnt(5)
	v_mfma_f32_16x16x32_bf16 v[102:105], v[130:133], v[192:195], v[102:105]
	s_waitcnt lgkmcnt(4)
	v_mfma_f32_16x16x32_bf16 v[94:97], v[130:133], v[196:199], v[94:97]
	s_waitcnt lgkmcnt(3)
	v_mfma_f32_16x16x32_bf16 v[86:89], v[130:133], v[200:203], v[86:89]
	s_waitcnt lgkmcnt(2)
	v_mfma_f32_16x16x32_bf16 v[78:81], v[130:133], v[204:207], v[78:81]
	s_waitcnt lgkmcnt(1)
	v_mfma_f32_16x16x32_bf16 v[70:73], v[130:133], v[208:211], v[70:73]
	s_bitcmp1_b32 s101, 0
	s_cbranch_scc0 .Lmyg1245_noB
	s_andn2_b32 s101, s101, 1
	s_setprio 3
	s_and_b32 s21, s20, 0x10000
	s_add_i32 s21, s21, 0
	s_add_i32 s22, s21, 0x2000
	s_add_i32 s21, s21, 0xa000
	v_add_u32_e32 v224, s21, v140
	v_lshl_add_u64 v[222:223], v[166:167], 0, s[14:15]
	v_readfirstlane_b32 s23, v224
	v_add_u32_e32 v224, s22, v140
	s_mov_b32 m0, s23
	v_readfirstlane_b32 s23, v224
	v_add_u32_e32 v224, s21, v142
	global_load_lds_dwordx4 v[222:223], off
	v_lshl_add_u64 v[222:223], v[156:157], 0, s[14:15]
	s_mov_b32 m0, s23
	v_readfirstlane_b32 s23, v224
	v_add_u32_e32 v224, s22, v142
	global_load_lds_dwordx4 v[222:223], off
	v_lshl_add_u64 v[222:223], v[164:165], 0, s[14:15]
	s_mov_b32 m0, s23
	v_readfirstlane_b32 s23, v224
	v_add_u32_e32 v224, s21, v144
	global_load_lds_dwordx4 v[222:223], off
	v_lshl_add_u64 v[222:223], v[154:155], 0, s[14:15]
	s_mov_b32 m0, s23
	v_readfirstlane_b32 s23, v224
	v_add_u32_e32 v224, s22, v144
	global_load_lds_dwordx4 v[222:223], off
	v_lshl_add_u64 v[222:223], v[160:161], 0, s[14:15]
	s_mov_b32 m0, s23
	v_readfirstlane_b32 s23, v224
	v_add_u32_e32 v224, s21, v146
	global_load_lds_dwordx4 v[222:223], off
	v_lshl_add_u64 v[222:223], v[152:153], 0, s[14:15]
	s_mov_b32 m0, s23
	v_readfirstlane_b32 s21, v224
	v_add_u32_e32 v224, s22, v146
	global_load_lds_dwordx4 v[222:223], off
	v_lshl_add_u64 v[222:223], v[158:159], 0, s[14:15]
	s_mov_b32 m0, s21
	v_readfirstlane_b32 s21, v224
	global_load_lds_dwordx4 v[222:223], off
	v_lshl_add_u64 v[222:223], v[150:151], 0, s[14:15]
	s_mov_b32 m0, s21
	s_nop 0
	global_load_lds_dwordx4 v[222:223], off
	s_setprio 0
; #define MFMA16(a, b, c) __builtin_amdgcn_mfma_f32_16x16x32_bf16((a), (b), (c), 0, 0, 0)
; DI void vm_wait0() { asm volatile("s_waitcnt vmcnt(0)" ::: "memory"); }
;   DI unsigned koff(int k) const { return (unsigned)((k >> 6) * EIN + (k & 63)); }
; DI void dma16(const void* g, unsigned char* l) { __builtin_amdgcn_global_load_lds((const unsigned*)g, (lds_u32_t*)(unsigned)(size_t)l, 16, 0, 0); }
; template <class AF, class EF>
; DI void gemm_run(unsigned char* lds, int wv, const AF& af, const bf16_t* __restrict__ Bt, int ldb, int M, int N, int K, const EF& ef, int blk_off) {
;     ...
;       if (kt + 1 < nk) {
;         unsigned char* nxt = sBase + ((kt + 1) & 1) * GST;
;         const int k0 = (kt + 1) << 6;
; #pragma unroll
;         for (int i = 0; i < 4; ++i) {
;           dma16(Ab + aoff[i] + af.koff(k0 + cch), nxt + 32768 + (i * 512 + tid) * 16);
;           dma16(Bt + boff[i] + (unsigned)k0, nxt + (i * 512 + tid) * 16);
;         }
;     ...
; #pragma unroll
;       for (int ks = 0; ks < 2; ++ks) {
;         bf16x8 wf[4], xf[8];
; #pragma unroll
;         for (int i = 0; i < 4; ++i) wf[i] = *(const bf16x8*)(cur + (wn * 64 + i * 16 + l15) * 128 + (((ks * 4 + q4) ^ swz) * 16));
; #pragma unroll
;         for (int j = 0; j < 8; ++j) xf[j] = *(const bf16x8*)(cur + 32768 + (wm * 128 + j * 16 + l15) * 128 + (((ks * 4 + q4) ^ swz) * 16));
; #pragma unroll
;         for (int i = 0; i < 4; ++i)
; #pragma unroll
;           for (int j = 0; j < 8; ++j) acc[i][j] = MFMA16(wf[i], xf[j], acc[i][j]);
;       }
;       vm_wait0();
;       __syncthreads();
;     }
.Lmyg1245_noB:
	s_waitcnt lgkmcnt(0)
	v_mfma_f32_16x16x32_bf16 v[122:125], v[226:229], v[134:137], v[122:125]
	ds_read_b128 v[130:133], v212 offset:12288
	v_mfma_f32_16x16x32_bf16 v[114:117], v[226:229], v[184:187], v[114:117]
	v_mfma_f32_16x16x32_bf16 v[106:109], v[226:229], v[188:191], v[106:109]
	v_mfma_f32_16x16x32_bf16 v[98:101], v[226:229], v[192:195], v[98:101]
	v_mfma_f32_16x16x32_bf16 v[90:93], v[226:229], v[196:199], v[90:93]
	v_mfma_f32_16x16x32_bf16 v[82:85], v[226:229], v[200:203], v[82:85]
	v_mfma_f32_16x16x32_bf16 v[74:77], v[226:229], v[204:207], v[74:77]
	v_mfma_f32_16x16x32_bf16 v[66:69], v[226:229], v[208:211], v[66:69]
	s_waitcnt lgkmcnt(0)
	v_mfma_f32_16x16x32_bf16 v[58:61], v[130:133], v[134:137], v[58:61]
	ds_read_b128 v[226:229], v212 offset:14336
	v_mfma_f32_16x16x32_bf16 v[50:53], v[130:133], v[184:187], v[50:53]
	v_add_u32_e32 v0, s100, v183
	v_mfma_f32_16x16x32_bf16 v[42:45], v[130:133], v[188:191], v[42:45]
	v_add3_u32 v212, v0, v180, v181
	v_mfma_f32_16x16x32_bf16 v[30:33], v[130:133], v[192:195], v[30:33]
	v_add3_u32 v0, v0, v182, v181
	v_mfma_f32_16x16x32_bf16 v[14:17], v[130:133], v[196:199], v[14:17]
	v_mfma_f32_16x16x32_bf16 v[10:13], v[130:133], v[200:203], v[10:13]
	v_mfma_f32_16x16x32_bf16 v[6:9], v[130:133], v[204:207], v[6:9]
	v_mfma_f32_16x16x32_bf16 v[2:5], v[130:133], v[208:211], v[2:5]
	s_waitcnt lgkmcnt(0)
	v_mfma_f32_16x16x32_bf16 v[54:57], v[226:229], v[184:187], v[54:57]
	ds_read_b128 v[130:133], v212 offset:8192
	ds_read_b128 v[184:187], v0 offset:43008
	v_mfma_f32_16x16x32_bf16 v[62:65], v[226:229], v[134:137], v[62:65]
	ds_read_b128 v[134:137], v0 offset:40960
	v_mfma_f32_16x16x32_bf16 v[46:49], v[226:229], v[188:191], v[46:49]
	ds_read_b128 v[188:191], v0 offset:45056
	v_mfma_f32_16x16x32_bf16 v[38:41], v[226:229], v[192:195], v[38:41]
	ds_read_b128 v[192:195], v0 offset:47104
	v_mfma_f32_16x16x32_bf16 v[26:29], v[226:229], v[196:199], v[26:29]
	ds_read_b128 v[196:199], v0 offset:49152
	v_mfma_f32_16x16x32_bf16 v[22:25], v[226:229], v[200:203], v[22:25]
	ds_read_b128 v[200:203], v0 offset:51200
	v_mfma_f32_16x16x32_bf16 v[34:37], v[226:229], v[204:207], v[34:37]
	ds_read_b128 v[204:207], v0 offset:53248
	v_mfma_f32_16x16x32_bf16 v[18:21], v[226:229], v[208:211], v[18:21]
	ds_read_b128 v[208:211], v0 offset:55296
	s_waitcnt lgkmcnt(7)
	v_mfma_f32_16x16x32_bf16 v[118:121], v[130:133], v[184:187], v[118:121]
	ds_read_b128 v[226:229], v212 offset:10240
	s_waitcnt lgkmcnt(7)
	v_mfma_f32_16x16x32_bf16 v[126:129], v[130:133], v[134:137], v[126:129]
	s_waitcnt lgkmcnt(6)
	v_mfma_f32_16x16x32_bf16 v[110:113], v[130:133], v[188:191], v[110:113]
	s_waitcnt lgkmcnt(5)
	v_mfma_f32_16x16x32_bf16 v[102:105], v[130:133], v[192:195], v[102:105]
	s_waitcnt lgkmcnt(4)
	v_mfma_f32_16x16x32_bf16 v[94:97], v[130:133], v[196:199], v[94:97]
	s_waitcnt lgkmcnt(3)
	v_mfma_f32_16x16x32_bf16 v[86:89], v[130:133], v[200:203], v[86:89]
	s_waitcnt lgkmcnt(2)
	v_mfma_f32_16x16x32_bf16 v[78:81], v[130:133], v[204:207], v[78:81]
	s_waitcnt lgkmcnt(1)
	v_mfma_f32_16x16x32_bf16 v[70:73], v[130:133], v[208:211], v[70:73]
	s_waitcnt lgkmcnt(0)
	v_mfma_f32_16x16x32_bf16 v[122:125], v[226:229], v[134:137], v[122:125]
	ds_read_b128 v[130:133], v212 offset:12288
	v_mfma_f32_16x16x32_bf16 v[114:117], v[226:229], v[184:187], v[114:117]
	v_mfma_f32_16x16x32_bf16 v[106:109], v[226:229], v[188:191], v[106:109]
	v_mfma_f32_16x16x32_bf16 v[98:101], v[226:229], v[192:195], v[98:101]
	v_mfma_f32_16x16x32_bf16 v[90:93], v[226:229], v[196:199], v[90:93]
	v_mfma_f32_16x16x32_bf16 v[82:85], v[226:229], v[200:203], v[82:85]
	v_mfma_f32_16x16x32_bf16 v[74:77], v[226:229], v[204:207], v[74:77]
	v_mfma_f32_16x16x32_bf16 v[66:69], v[226:229], v[208:211], v[66:69]
	s_waitcnt lgkmcnt(0)
	v_mfma_f32_16x16x32_bf16 v[58:61], v[130:133], v[134:137], v[58:61]
	ds_read_b128 v[226:229], v212 offset:14336
	v_mfma_f32_16x16x32_bf16 v[50:53], v[130:133], v[184:187], v[50:53]
	v_mfma_f32_16x16x32_bf16 v[42:45], v[130:133], v[188:191], v[42:45]
	v_mfma_f32_16x16x32_bf16 v[30:33], v[130:133], v[192:195], v[30:33]
	v_mfma_f32_16x16x32_bf16 v[14:17], v[130:133], v[196:199], v[14:17]
	v_mfma_f32_16x16x32_bf16 v[10:13], v[130:133], v[200:203], v[10:13]
	v_mfma_f32_16x16x32_bf16 v[6:9], v[130:133], v[204:207], v[6:9]
	v_mfma_f32_16x16x32_bf16 v[2:5], v[130:133], v[208:211], v[2:5]
	s_waitcnt vmcnt(0) lgkmcnt(0)
	s_barrier
	s_add_u32 s14, s14, 0x80
	s_addc_u32 s15, s15, 0
	s_add_i32 s20, s20, 0x10000
	s_add_i32 s19, s19, 1
	s_cmpk_eq_i32 s14, 0x800
	s_cbranch_scc1 .Lmyg1245_tail
	s_add_i32 s100, s20, 0xffff0000
	s_and_b32 s100, s100, 0x10000
	v_add_u32_e32 v0, s100, v179
	v_add3_u32 v212, v0, v180, v181
	v_add3_u32 v0, v0, v182, v181
	s_cmp_gt_u32 s19, 14
	s_cbranch_scc1 .Lmyg1245_nodma
	s_bitcmp1_b32 s101, 1
	s_cbranch_scc1 .Lmyg1245_defer
	s_setprio 3
	s_and_b32 s21, s20, 0x10000
	s_add_i32 s21, s21, 0
	s_add_i32 s22, s21, 0x2000
	s_add_i32 s21, s21, 0xa000
	v_add_u32_e32 v224, s21, v140
	v_lshl_add_u64 v[222:223], v[166:167], 0, s[14:15]
	v_readfirstlane_b32 s23, v224
	v_add_u32_e32 v224, s22, v140
	s_mov_b32 m0, s23
	v_readfirstlane_b32 s23, v224
	v_add_u32_e32 v224, s21, v142
	global_load_lds_dwordx4 v[222:223], off
	v_lshl_add_u64 v[222:223], v[156:157], 0, s[14:15]
	s_mov_b32 m0, s23
	v_readfirstlane_b32 s23, v224
	v_add_u32_e32 v224, s22, v142
	global_load_lds_dwordx4 v[222:223], off
	v_lshl_add_u64 v[222:223], v[164:165], 0, s[14:15]
	s_mov_b32 m0, s23
	v_readfirstlane_b32 s23, v224
	v_add_u32_e32 v224, s21, v144
	global_load_lds_dwordx4 v[222:223], off
	v_lshl_add_u64 v[222:223], v[154:155], 0, s[14:15]
	s_mov_b32 m0, s23
	v_readfirstlane_b32 s23, v224
	v_add_u32_e32 v224, s22, v144
	global_load_lds_dwordx4 v[222:223], off
	v_lshl_add_u64 v[222:223], v[160:161], 0, s[14:15]
	s_mov_b32 m0, s23
	v_readfirstlane_b32 s23, v224
	v_add_u32_e32 v224, s21, v146
	global_load_lds_dwordx4 v[222:223], off
	v_lshl_add_u64 v[222:223], v[152:153], 0, s[14:15]
	s_mov_b32 m0, s23
	v_readfirstlane_b32 s21, v224
	v_add_u32_e32 v224, s22, v146
	global_load_lds_dwordx4 v[222:223], off
	v_lshl_add_u64 v[222:223], v[158:159], 0, s[14:15]
	s_mov_b32 m0, s21
	v_readfirstlane_b32 s21, v224
	global_load_lds_dwordx4 v[222:223], off
	v_lshl_add_u64 v[222:223], v[150:151], 0, s[14:15]
	s_mov_b32 m0, s21
	s_nop 0
	global_load_lds_dwordx4 v[222:223], off
	s_setprio 0
	s_branch .Lmyg1245_nodma

; #define MFMA16(a, b, c) __builtin_amdgcn_mfma_f32_16x16x32_bf16((a), (b), (c), 0, 0, 0)
;   DI unsigned koff(int k) const { return (unsigned)((k >> 6) * EIN + (k & 63)); }
; DI void dma16(const void* g, unsigned char* l) { __builtin_amdgcn_global_load_lds((const unsigned*)g, (lds_u32_t*)(unsigned)(size_t)l, 16, 0, 0); }
; template <class AF, class EF>
; DI void gemm_run(unsigned char* lds, int wv, const AF& af, const bf16_t* __restrict__ Bt, int ldb, int M, int N, int K, const EF& ef, int blk_off) {
;     ...
;     for (int kt = 0; kt < nk; ++kt) {
;       unsigned char* cur = sBase + (kt & 1) * GST;
;       if (kt + 1 < nk) {
;         unsigned char* nxt = sBase + ((kt + 1) & 1) * GST;
;         const int k0 = (kt + 1) << 6;
; #pragma unroll
;         for (int i = 0; i < 4; ++i) {
;           dma16(Ab + aoff[i] + af.koff(k0 + cch), nxt + 32768 + (i * 512 + tid) * 16);
;           dma16(Bt + boff[i] + (unsigned)k0, nxt + (i * 512 + tid) * 16);
;         }
;       }
; #pragma unroll
;       for (int ks = 0; ks < 2; ++ks) {
;         bf16x8 wf[4], xf[8];
; #pragma unroll
;         for (int i = 0; i < 4; ++i) wf[i] = *(const bf16x8*)(cur + (wn * 64 + i * 16 + l15) * 128 + (((ks * 4 + q4) ^ swz) * 16));
; #pragma unroll
;         for (int j = 0; j < 8; ++j) xf[j] = *(const bf16x8*)(cur + 32768 + (wm * 128 + j * 16 + l15) * 128 + (((ks * 4 + q4) ^ swz) * 16));
; #pragma unroll
;         for (int i = 0; i < 4; ++i)
; #pragma unroll
;           for (int j = 0; j < 8; ++j) acc[i][j] = MFMA16(wf[i], xf[j], acc[i][j]);
;       }
.Lmyg1267_loop:
	s_waitcnt lgkmcnt(7)
	v_mfma_f32_16x16x32_bf16 v[126:129], v[130:133], v[180:183], v[126:129]
	ds_read_b128 v[226:229], v179 offset:10240
	s_waitcnt lgkmcnt(7)
	v_mfma_f32_16x16x32_bf16 v[118:121], v[130:133], v[184:187], v[118:121]
	s_waitcnt lgkmcnt(6)
	v_mfma_f32_16x16x32_bf16 v[110:113], v[130:133], v[188:191], v[110:113]
	s_waitcnt lgkmcnt(5)
	v_mfma_f32_16x16x32_bf16 v[102:105], v[130:133], v[192:195], v[102:105]
	s_waitcnt lgkmcnt(4)
	v_mfma_f32_16x16x32_bf16 v[94:97], v[130:133], v[196:199], v[94:97]
	s_waitcnt lgkmcnt(3)
	v_mfma_f32_16x16x32_bf16 v[86:89], v[130:133], v[200:203], v[86:89]
	s_waitcnt lgkmcnt(2)
	v_mfma_f32_16x16x32_bf16 v[78:81], v[130:133], v[204:207], v[78:81]
	s_waitcnt lgkmcnt(1)
	v_mfma_f32_16x16x32_bf16 v[70:73], v[130:133], v[208:211], v[70:73]
	s_bitcmp1_b32 s101, 0
	s_cbranch_scc0 .Lmyg1267_noB
	s_andn2_b32 s101, s101, 1
	s_setprio 3
	s_and_b32 s16, s15, 0x10000
	s_add_i32 s16, s16, 0
	s_add_i32 s17, s16, 0x2000
	s_add_i32 s16, s16, 0xa000
	v_add_u32_e32 v224, s16, v136
	v_lshl_add_u64 v[222:223], v[160:161], 0, s[10:11]
	v_readfirstlane_b32 s18, v224
	v_add_u32_e32 v224, s17, v136
	s_mov_b32 m0, s18
	v_readfirstlane_b32 s18, v224
	v_add_u32_e32 v224, s16, v138
	global_load_lds_dwordx4 v[222:223], off
	v_lshl_add_u64 v[222:223], v[152:153], 0, s[10:11]
	s_mov_b32 m0, s18
	v_readfirstlane_b32 s18, v224
	v_add_u32_e32 v224, s17, v138
	global_load_lds_dwordx4 v[222:223], off
	v_lshl_add_u64 v[222:223], v[158:159], 0, s[10:11]
	s_mov_b32 m0, s18
	v_readfirstlane_b32 s18, v224
	v_add_u32_e32 v224, s16, v140
	global_load_lds_dwordx4 v[222:223], off
	v_lshl_add_u64 v[222:223], v[150:151], 0, s[10:11]
	s_mov_b32 m0, s18
	v_readfirstlane_b32 s18, v224
	v_add_u32_e32 v224, s17, v140
	global_load_lds_dwordx4 v[222:223], off
	v_lshl_add_u64 v[222:223], v[156:157], 0, s[10:11]
	s_mov_b32 m0, s18
	v_readfirstlane_b32 s18, v224
	v_add_u32_e32 v224, s16, v142
	global_load_lds_dwordx4 v[222:223], off
	v_lshl_add_u64 v[222:223], v[148:149], 0, s[10:11]
	s_mov_b32 m0, s18
	v_readfirstlane_b32 s16, v224
	v_add_u32_e32 v224, s17, v142
	global_load_lds_dwordx4 v[222:223], off
	v_lshl_add_u64 v[222:223], v[154:155], 0, s[10:11]
	s_mov_b32 m0, s16
	v_readfirstlane_b32 s16, v224
	global_load_lds_dwordx4 v[222:223], off
	v_lshl_add_u64 v[222:223], v[146:147], 0, s[10:11]
	s_mov_b32 m0, s16
	s_nop 0
	global_load_lds_dwordx4 v[222:223], off
	s_setprio 0
; #define MFMA16(a, b, c) __builtin_amdgcn_mfma_f32_16x16x32_bf16((a), (b), (c), 0, 0, 0)
; DI void vm_wait0() { asm volatile("s_waitcnt vmcnt(0)" ::: "memory"); }
;   DI unsigned koff(int k) const { return (unsigned)((k >> 6) * EIN + (k & 63)); }
; DI void dma16(const void* g, unsigned char* l) { __builtin_amdgcn_global_load_lds((const unsigned*)g, (lds_u32_t*)(unsigned)(size_t)l, 16, 0, 0); }
; template <class AF, class EF>
; DI void gemm_run(unsigned char* lds, int wv, const AF& af, const bf16_t* __restrict__ Bt, int ldb, int M, int N, int K, const EF& ef, int blk_off) {
;     ...
;       if (kt + 1 < nk) {
;         unsigned char* nxt = sBase + ((kt + 1) & 1) * GST;
;         const int k0 = (kt + 1) << 6;
; #pragma unroll
;         for (int i = 0; i < 4; ++i) {
;           dma16(Ab + aoff[i] + af.koff(k0 + cch), nxt + 32768 + (i * 512 + tid) * 16);
;           dma16(Bt + boff[i] + (unsigned)k0, nxt + (i * 512 + tid) * 16);
;         }
;     ...
; #pragma unroll
;       for (int ks = 0; ks < 2; ++ks) {
;         bf16x8 wf[4], xf[8];
; #pragma unroll
;         for (int i = 0; i < 4; ++i) wf[i] = *(const bf16x8*)(cur + (wn * 64 + i * 16 + l15) * 128 + (((ks * 4 + q4) ^ swz) * 16));
; #pragma unroll
;         for (int j = 0; j < 8; ++j) xf[j] = *(const bf16x8*)(cur + 32768 + (wm * 128 + j * 16 + l15) * 128 + (((ks * 4 + q4) ^ swz) * 16));
; #pragma unroll
;         for (int i = 0; i < 4; ++i)
; #pragma unroll
;           for (int j = 0; j < 8; ++j) acc[i][j] = MFMA16(wf[i], xf[j], acc[i][j]);
;       }
;       vm_wait0();
;       __syncthreads();
;     }
.Lmyg1267_noB:
	s_waitcnt lgkmcnt(0)
	v_mfma_f32_16x16x32_bf16 v[122:125], v[226:229], v[180:183], v[122:125]
	ds_read_b128 v[130:133], v179 offset:12288
	v_mfma_f32_16x16x32_bf16 v[114:117], v[226:229], v[184:187], v[114:117]
	v_mfma_f32_16x16x32_bf16 v[106:109], v[226:229], v[188:191], v[106:109]
	v_mfma_f32_16x16x32_bf16 v[98:101], v[226:229], v[192:195], v[98:101]
	v_mfma_f32_16x16x32_bf16 v[90:93], v[226:229], v[196:199], v[90:93]
	v_mfma_f32_16x16x32_bf16 v[82:85], v[226:229], v[200:203], v[82:85]
	v_mfma_f32_16x16x32_bf16 v[74:77], v[226:229], v[204:207], v[74:77]
	v_mfma_f32_16x16x32_bf16 v[62:65], v[226:229], v[208:211], v[62:65]
	s_waitcnt lgkmcnt(0)
	v_mfma_f32_16x16x32_bf16 v[54:57], v[130:133], v[180:183], v[54:57]
	ds_read_b128 v[226:229], v179 offset:14336
	v_mfma_f32_16x16x32_bf16 v[46:49], v[130:133], v[184:187], v[46:49]
	v_add_u32_e32 v0, s100, v178
	v_mfma_f32_16x16x32_bf16 v[38:41], v[130:133], v[188:191], v[38:41]
	v_add3_u32 v179, v0, v175, v176
	v_mfma_f32_16x16x32_bf16 v[26:29], v[130:133], v[192:195], v[26:29]
	v_add3_u32 v0, v0, v177, v176
	v_mfma_f32_16x16x32_bf16 v[14:17], v[130:133], v[196:199], v[14:17]
	v_mfma_f32_16x16x32_bf16 v[10:13], v[130:133], v[200:203], v[10:13]
	v_mfma_f32_16x16x32_bf16 v[6:9], v[130:133], v[204:207], v[6:9]
	v_mfma_f32_16x16x32_bf16 v[2:5], v[130:133], v[208:211], v[2:5]
	s_waitcnt lgkmcnt(0)
	v_mfma_f32_16x16x32_bf16 v[66:69], v[226:229], v[180:183], v[66:69]
	ds_read_b128 v[130:133], v179 offset:8192
	ds_read_b128 v[180:183], v0 offset:40960
	v_mfma_f32_16x16x32_bf16 v[58:61], v[226:229], v[184:187], v[58:61]
	ds_read_b128 v[184:187], v0 offset:43008
	v_mfma_f32_16x16x32_bf16 v[50:53], v[226:229], v[188:191], v[50:53]
	ds_read_b128 v[188:191], v0 offset:45056
	v_mfma_f32_16x16x32_bf16 v[42:45], v[226:229], v[192:195], v[42:45]
	ds_read_b128 v[192:195], v0 offset:47104
	v_mfma_f32_16x16x32_bf16 v[30:33], v[226:229], v[196:199], v[30:33]
	ds_read_b128 v[196:199], v0 offset:49152
	v_mfma_f32_16x16x32_bf16 v[22:25], v[226:229], v[200:203], v[22:25]
	ds_read_b128 v[200:203], v0 offset:51200
	v_mfma_f32_16x16x32_bf16 v[18:21], v[226:229], v[204:207], v[18:21]
	ds_read_b128 v[204:207], v0 offset:53248
	v_mfma_f32_16x16x32_bf16 v[34:37], v[226:229], v[208:211], v[34:37]
	ds_read_b128 v[208:211], v0 offset:55296
	s_waitcnt lgkmcnt(7)
	v_mfma_f32_16x16x32_bf16 v[126:129], v[130:133], v[180:183], v[126:129]
	ds_read_b128 v[226:229], v179 offset:10240
	s_waitcnt lgkmcnt(7)
	v_mfma_f32_16x16x32_bf16 v[118:121], v[130:133], v[184:187], v[118:121]
	s_waitcnt lgkmcnt(6)
	v_mfma_f32_16x16x32_bf16 v[110:113], v[130:133], v[188:191], v[110:113]
	s_waitcnt lgkmcnt(5)
	v_mfma_f32_16x16x32_bf16 v[102:105], v[130:133], v[192:195], v[102:105]
	s_waitcnt lgkmcnt(4)
	v_mfma_f32_16x16x32_bf16 v[94:97], v[130:133], v[196:199], v[94:97]
	s_waitcnt lgkmcnt(3)
	v_mfma_f32_16x16x32_bf16 v[86:89], v[130:133], v[200:203], v[86:89]
	s_waitcnt lgkmcnt(2)
	v_mfma_f32_16x16x32_bf16 v[78:81], v[130:133], v[204:207], v[78:81]
	s_waitcnt lgkmcnt(1)
	v_mfma_f32_16x16x32_bf16 v[70:73], v[130:133], v[208:211], v[70:73]
	s_waitcnt lgkmcnt(0)
	v_mfma_f32_16x16x32_bf16 v[122:125], v[226:229], v[180:183], v[122:125]
	ds_read_b128 v[130:133], v179 offset:12288
	v_mfma_f32_16x16x32_bf16 v[114:117], v[226:229], v[184:187], v[114:117]
	v_mfma_f32_16x16x32_bf16 v[106:109], v[226:229], v[188:191], v[106:109]
	v_mfma_f32_16x16x32_bf16 v[98:101], v[226:229], v[192:195], v[98:101]
	v_mfma_f32_16x16x32_bf16 v[90:93], v[226:229], v[196:199], v[90:93]
	v_mfma_f32_16x16x32_bf16 v[82:85], v[226:229], v[200:203], v[82:85]
	v_mfma_f32_16x16x32_bf16 v[74:77], v[226:229], v[204:207], v[74:77]
	v_mfma_f32_16x16x32_bf16 v[62:65], v[226:229], v[208:211], v[62:65]
	s_waitcnt lgkmcnt(0)
	v_mfma_f32_16x16x32_bf16 v[54:57], v[130:133], v[180:183], v[54:57]
	ds_read_b128 v[226:229], v179 offset:14336
	v_mfma_f32_16x16x32_bf16 v[46:49], v[130:133], v[184:187], v[46:49]
	v_mfma_f32_16x16x32_bf16 v[38:41], v[130:133], v[188:191], v[38:41]
	v_mfma_f32_16x16x32_bf16 v[26:29], v[130:133], v[192:195], v[26:29]
	v_mfma_f32_16x16x32_bf16 v[14:17], v[130:133], v[196:199], v[14:17]
	v_mfma_f32_16x16x32_bf16 v[10:13], v[130:133], v[200:203], v[10:13]
	v_mfma_f32_16x16x32_bf16 v[6:9], v[130:133], v[204:207], v[6:9]
	v_mfma_f32_16x16x32_bf16 v[2:5], v[130:133], v[208:211], v[2:5]
	s_waitcnt vmcnt(0) lgkmcnt(0)
	s_barrier
	s_add_u32 s10, s10, 0x80
	s_addc_u32 s11, s11, 0
	s_add_i32 s15, s15, 0x10000
	s_cmpk_eq_i32 s10, 0x800
	s_cbranch_scc1 .Lmyg1267_tail
	s_add_i32 s100, s15, 0xffff0000
	s_and_b32 s100, s100, 0x10000
	v_add_u32_e32 v0, s100, v174
	v_add3_u32 v179, v0, v175, v176
	v_add3_u32 v0, v0, v177, v176
	s_cmpk_eq_i32 s10, 0x780
	s_cbranch_scc1 .Lmyg1267_nodma
	s_bitcmp1_b32 s101, 1
	s_cbranch_scc1 .Lmyg1267_defer
	s_setprio 3
	s_and_b32 s16, s15, 0x10000
	s_add_i32 s16, s16, 0
	s_add_i32 s17, s16, 0x2000
	s_add_i32 s16, s16, 0xa000
	v_add_u32_e32 v224, s16, v136
	v_lshl_add_u64 v[222:223], v[160:161], 0, s[10:11]
	v_readfirstlane_b32 s18, v224
	v_add_u32_e32 v224, s17, v136
	s_mov_b32 m0, s18
	v_readfirstlane_b32 s18, v224
	v_add_u32_e32 v224, s16, v138
	global_load_lds_dwordx4 v[222:223], off
	v_lshl_add_u64 v[222:223], v[152:153], 0, s[10:11]
	s_mov_b32 m0, s18
	v_readfirstlane_b32 s18, v224
	v_add_u32_e32 v224, s17, v138
	global_load_lds_dwordx4 v[222:223], off
	v_lshl_add_u64 v[222:223], v[158:159], 0, s[10:11]
	s_mov_b32 m0, s18
	v_readfirstlane_b32 s18, v224
	v_add_u32_e32 v224, s16, v140
	global_load_lds_dwordx4 v[222:223], off
	v_lshl_add_u64 v[222:223], v[150:151], 0, s[10:11]
	s_mov_b32 m0, s18
	v_readfirstlane_b32 s18, v224
	v_add_u32_e32 v224, s17, v140
	global_load_lds_dwordx4 v[222:223], off
	v_lshl_add_u64 v[222:223], v[156:157], 0, s[10:11]
	s_mov_b32 m0, s18
	v_readfirstlane_b32 s18, v224
	v_add_u32_e32 v224, s16, v142
	global_load_lds_dwordx4 v[222:223], off
	v_lshl_add_u64 v[222:223], v[148:149], 0, s[10:11]
	s_mov_b32 m0, s18
	v_readfirstlane_b32 s16, v224
	v_add_u32_e32 v224, s17, v142
	global_load_lds_dwordx4 v[222:223], off
	v_lshl_add_u64 v[222:223], v[154:155], 0, s[10:11]
	s_mov_b32 m0, s16
	v_readfirstlane_b32 s16, v224
	global_load_lds_dwordx4 v[222:223], off
	v_lshl_add_u64 v[222:223], v[146:147], 0, s[10:11]
	s_mov_b32 m0, s16
	s_nop 0
	global_load_lds_dwordx4 v[222:223], off
	s_setprio 0
	s_branch .Lmyg1267_nodma

; #define MFMA16(a, b, c) __builtin_amdgcn_mfma_f32_16x16x32_bf16((a), (b), (c), 0, 0, 0)
;   DI unsigned koff(int k) const { return (unsigned)((k >> 6) * EIN + (k & 63)); }
; DI void dma16(const void* g, unsigned char* l) { __builtin_amdgcn_global_load_lds((const unsigned*)g, (lds_u32_t*)(unsigned)(size_t)l, 16, 0, 0); }
; template <class AF, class EF>
; DI void gemm_run(unsigned char* lds, int wv, const AF& af, const bf16_t* __restrict__ Bt, int ldb, int M, int N, int K, const EF& ef, int blk_off) {
;     ...
;     for (int kt = 0; kt < nk; ++kt) {
;       unsigned char* cur = sBase + (kt & 1) * GST;
;       if (kt + 1 < nk) {
;         unsigned char* nxt = sBase + ((kt + 1) & 1) * GST;
;         const int k0 = (kt + 1) << 6;
; #pragma unroll
;         for (int i = 0; i < 4; ++i) {
;           dma16(Ab + aoff[i] + af.koff(k0 + cch), nxt + 32768 + (i * 512 + tid) * 16);
;           dma16(Bt + boff[i] + (unsigned)k0, nxt + (i * 512 + tid) * 16);
;         }
;       }
; #pragma unroll
;       for (int ks = 0; ks < 2; ++ks) {
;         bf16x8 wf[4], xf[8];
; #pragma unroll
;         for (int i = 0; i < 4; ++i) wf[i] = *(const bf16x8*)(cur + (wn * 64 + i * 16 + l15) * 128 + (((ks * 4 + q4) ^ swz) * 16));
; #pragma unroll
;         for (int j = 0; j < 8; ++j) xf[j] = *(const bf16x8*)(cur + 32768 + (wm * 128 + j * 16 + l15) * 128 + (((ks * 4 + q4) ^ swz) * 16));
; #pragma unroll
;         for (int i = 0; i < 4; ++i)
; #pragma unroll
;           for (int j = 0; j < 8; ++j) acc[i][j] = MFMA16(wf[i], xf[j], acc[i][j]);
;       }
.Lmyg1279_loop:
	s_waitcnt lgkmcnt(7)
	v_mfma_f32_16x16x32_bf16 v[118:121], v[130:133], v[184:187], v[118:121]
	ds_read_b128 v[226:229], v212 offset:10240
	s_waitcnt lgkmcnt(7)
	v_mfma_f32_16x16x32_bf16 v[126:129], v[130:133], v[134:137], v[126:129]
	s_waitcnt lgkmcnt(6)
	v_mfma_f32_16x16x32_bf16 v[110:113], v[130:133], v[188:191], v[110:113]
	s_waitcnt lgkmcnt(5)
	v_mfma_f32_16x16x32_bf16 v[102:105], v[130:133], v[192:195], v[102:105]
	s_waitcnt lgkmcnt(4)
	v_mfma_f32_16x16x32_bf16 v[94:97], v[130:133], v[196:199], v[94:97]
	s_waitcnt lgkmcnt(3)
	v_mfma_f32_16x16x32_bf16 v[86:89], v[130:133], v[200:203], v[86:89]
	s_waitcnt lgkmcnt(2)
	v_mfma_f32_16x16x32_bf16 v[78:81], v[130:133], v[204:207], v[78:81]
	s_waitcnt lgkmcnt(1)
	v_mfma_f32_16x16x32_bf16 v[70:73], v[130:133], v[208:211], v[70:73]
	s_bitcmp1_b32 s101, 0
	s_cbranch_scc0 .Lmyg1279_noB
	s_andn2_b32 s101, s101, 1
	s_setprio 3
	s_and_b32 s23, s22, 0x10000
	s_add_i32 s23, s23, 0
	s_add_i32 s24, s23, 0x2000
	s_add_i32 s23, s23, 0xa000
	v_add_u32_e32 v224, s23, v140
	v_lshl_add_u64 v[222:223], v[166:167], 0, s[16:17]
	v_readfirstlane_b32 s25, v224
	v_add_u32_e32 v224, s24, v140
	s_mov_b32 m0, s25
	v_readfirstlane_b32 s25, v224
	v_add_u32_e32 v224, s23, v142
	global_load_lds_dwordx4 v[222:223], off
	v_lshl_add_u64 v[222:223], v[156:157], 0, s[16:17]
	s_mov_b32 m0, s25
	v_readfirstlane_b32 s25, v224
	v_add_u32_e32 v224, s24, v142
	global_load_lds_dwordx4 v[222:223], off
	v_lshl_add_u64 v[222:223], v[164:165], 0, s[16:17]
	s_mov_b32 m0, s25
	v_readfirstlane_b32 s25, v224
	v_add_u32_e32 v224, s23, v144
	global_load_lds_dwordx4 v[222:223], off
	v_lshl_add_u64 v[222:223], v[154:155], 0, s[16:17]
	s_mov_b32 m0, s25
	v_readfirstlane_b32 s25, v224
	v_add_u32_e32 v224, s24, v144
	global_load_lds_dwordx4 v[222:223], off
	v_lshl_add_u64 v[222:223], v[160:161], 0, s[16:17]
	s_mov_b32 m0, s25
	v_readfirstlane_b32 s25, v224
	v_add_u32_e32 v224, s23, v146
	global_load_lds_dwordx4 v[222:223], off
	v_lshl_add_u64 v[222:223], v[152:153], 0, s[16:17]
	s_mov_b32 m0, s25
	v_readfirstlane_b32 s23, v224
	v_add_u32_e32 v224, s24, v146
	global_load_lds_dwordx4 v[222:223], off
	v_lshl_add_u64 v[222:223], v[158:159], 0, s[16:17]
	s_mov_b32 m0, s23
	v_readfirstlane_b32 s23, v224
	global_load_lds_dwordx4 v[222:223], off
	v_lshl_add_u64 v[222:223], v[150:151], 0, s[16:17]
	s_mov_b32 m0, s23
	s_nop 0
	global_load_lds_dwordx4 v[222:223], off
	s_setprio 0
; #define MFMA16(a, b, c) __builtin_amdgcn_mfma_f32_16x16x32_bf16((a), (b), (c), 0, 0, 0)
; DI void vm_wait0() { asm volatile("s_waitcnt vmcnt(0)" ::: "memory"); }
;   DI unsigned koff(int k) const { return (unsigned)((k >> 6) * EIN + (k & 63)); }
; DI void dma16(const void* g, unsigned char* l) { __builtin_amdgcn_global_load_lds((const unsigned*)g, (lds_u32_t*)(unsigned)(size_t)l, 16, 0, 0); }
; template <class AF, class EF>
; DI void gemm_run(unsigned char* lds, int wv, const AF& af, const bf16_t* __restrict__ Bt, int ldb, int M, int N, int K, const EF& ef, int blk_off) {
;     ...
;       if (kt + 1 < nk) {
;         unsigned char* nxt = sBase + ((kt + 1) & 1) * GST;
;         const int k0 = (kt + 1) << 6;
; #pragma unroll
;         for (int i = 0; i < 4; ++i) {
;           dma16(Ab + aoff[i] + af.koff(k0 + cch), nxt + 32768 + (i * 512 + tid) * 16);
;           dma16(Bt + boff[i] + (unsigned)k0, nxt + (i * 512 + tid) * 16);
;         }
;     ...
; #pragma unroll
;       for (int ks = 0; ks < 2; ++ks) {
;         bf16x8 wf[4], xf[8];
; #pragma unroll
;         for (int i = 0; i < 4; ++i) wf[i] = *(const bf16x8*)(cur + (wn * 64 + i * 16 + l15) * 128 + (((ks * 4 + q4) ^ swz) * 16));
; #pragma unroll
;         for (int j = 0; j < 8; ++j) xf[j] = *(const bf16x8*)(cur + 32768 + (wm * 128 + j * 16 + l15) * 128 + (((ks * 4 + q4) ^ swz) * 16));
; #pragma unroll
;         for (int i = 0; i < 4; ++i)
; #pragma unroll
;           for (int j = 0; j < 8; ++j) acc[i][j] = MFMA16(wf[i], xf[j], acc[i][j]);
;       }
;       vm_wait0();
;       __syncthreads();
;     }
.Lmyg1279_noB:
	s_waitcnt lgkmcnt(0)
	v_mfma_f32_16x16x32_bf16 v[122:125], v[226:229], v[134:137], v[122:125]
	ds_read_b128 v[130:133], v212 offset:12288
	v_mfma_f32_16x16x32_bf16 v[114:117], v[226:229], v[184:187], v[114:117]
	v_mfma_f32_16x16x32_bf16 v[106:109], v[226:229], v[188:191], v[106:109]
	v_mfma_f32_16x16x32_bf16 v[98:101], v[226:229], v[192:195], v[98:101]
	v_mfma_f32_16x16x32_bf16 v[90:93], v[226:229], v[196:199], v[90:93]
	v_mfma_f32_16x16x32_bf16 v[82:85], v[226:229], v[200:203], v[82:85]
	v_mfma_f32_16x16x32_bf16 v[74:77], v[226:229], v[204:207], v[74:77]
	v_mfma_f32_16x16x32_bf16 v[66:69], v[226:229], v[208:211], v[66:69]
	s_waitcnt lgkmcnt(0)
	v_mfma_f32_16x16x32_bf16 v[58:61], v[130:133], v[134:137], v[58:61]
	ds_read_b128 v[226:229], v212 offset:14336
	v_mfma_f32_16x16x32_bf16 v[50:53], v[130:133], v[184:187], v[50:53]
	v_add_u32_e32 v0, s100, v183
	v_mfma_f32_16x16x32_bf16 v[42:45], v[130:133], v[188:191], v[42:45]
	v_add3_u32 v212, v0, v180, v181
	v_mfma_f32_16x16x32_bf16 v[30:33], v[130:133], v[192:195], v[30:33]
	v_add3_u32 v0, v0, v182, v181
	v_mfma_f32_16x16x32_bf16 v[14:17], v[130:133], v[196:199], v[14:17]
	v_mfma_f32_16x16x32_bf16 v[10:13], v[130:133], v[200:203], v[10:13]
	v_mfma_f32_16x16x32_bf16 v[6:9], v[130:133], v[204:207], v[6:9]
	v_mfma_f32_16x16x32_bf16 v[2:5], v[130:133], v[208:211], v[2:5]
	s_waitcnt lgkmcnt(0)
	v_mfma_f32_16x16x32_bf16 v[54:57], v[226:229], v[184:187], v[54:57]
	ds_read_b128 v[130:133], v212 offset:8192
	ds_read_b128 v[184:187], v0 offset:43008
	v_mfma_f32_16x16x32_bf16 v[62:65], v[226:229], v[134:137], v[62:65]
	ds_read_b128 v[134:137], v0 offset:40960
	v_mfma_f32_16x16x32_bf16 v[46:49], v[226:229], v[188:191], v[46:49]
	ds_read_b128 v[188:191], v0 offset:45056
	v_mfma_f32_16x16x32_bf16 v[38:41], v[226:229], v[192:195], v[38:41]
	ds_read_b128 v[192:195], v0 offset:47104
	v_mfma_f32_16x16x32_bf16 v[26:29], v[226:229], v[196:199], v[26:29]
	ds_read_b128 v[196:199], v0 offset:49152
	v_mfma_f32_16x16x32_bf16 v[22:25], v[226:229], v[200:203], v[22:25]
	ds_read_b128 v[200:203], v0 offset:51200
	v_mfma_f32_16x16x32_bf16 v[34:37], v[226:229], v[204:207], v[34:37]
	ds_read_b128 v[204:207], v0 offset:53248
	v_mfma_f32_16x16x32_bf16 v[18:21], v[226:229], v[208:211], v[18:21]
	ds_read_b128 v[208:211], v0 offset:55296
	s_waitcnt lgkmcnt(7)
	v_mfma_f32_16x16x32_bf16 v[118:121], v[130:133], v[184:187], v[118:121]
	ds_read_b128 v[226:229], v212 offset:10240
	s_waitcnt lgkmcnt(7)
	v_mfma_f32_16x16x32_bf16 v[126:129], v[130:133], v[134:137], v[126:129]
	s_waitcnt lgkmcnt(6)
	v_mfma_f32_16x16x32_bf16 v[110:113], v[130:133], v[188:191], v[110:113]
	s_waitcnt lgkmcnt(5)
	v_mfma_f32_16x16x32_bf16 v[102:105], v[130:133], v[192:195], v[102:105]
	s_waitcnt lgkmcnt(4)
	v_mfma_f32_16x16x32_bf16 v[94:97], v[130:133], v[196:199], v[94:97]
	s_waitcnt lgkmcnt(3)
	v_mfma_f32_16x16x32_bf16 v[86:89], v[130:133], v[200:203], v[86:89]
	s_waitcnt lgkmcnt(2)
	v_mfma_f32_16x16x32_bf16 v[78:81], v[130:133], v[204:207], v[78:81]
	s_waitcnt lgkmcnt(1)
	v_mfma_f32_16x16x32_bf16 v[70:73], v[130:133], v[208:211], v[70:73]
	s_waitcnt lgkmcnt(0)
	v_mfma_f32_16x16x32_bf16 v[122:125], v[226:229], v[134:137], v[122:125]
	ds_read_b128 v[130:133], v212 offset:12288
	v_mfma_f32_16x16x32_bf16 v[114:117], v[226:229], v[184:187], v[114:117]
	v_mfma_f32_16x16x32_bf16 v[106:109], v[226:229], v[188:191], v[106:109]
	v_mfma_f32_16x16x32_bf16 v[98:101], v[226:229], v[192:195], v[98:101]
	v_mfma_f32_16x16x32_bf16 v[90:93], v[226:229], v[196:199], v[90:93]
	v_mfma_f32_16x16x32_bf16 v[82:85], v[226:229], v[200:203], v[82:85]
	v_mfma_f32_16x16x32_bf16 v[74:77], v[226:229], v[204:207], v[74:77]
	v_mfma_f32_16x16x32_bf16 v[66:69], v[226:229], v[208:211], v[66:69]
	s_waitcnt lgkmcnt(0)
	v_mfma_f32_16x16x32_bf16 v[58:61], v[130:133], v[134:137], v[58:61]
	ds_read_b128 v[226:229], v212 offset:14336
	v_mfma_f32_16x16x32_bf16 v[50:53], v[130:133], v[184:187], v[50:53]
	v_mfma_f32_16x16x32_bf16 v[42:45], v[130:133], v[188:191], v[42:45]
	v_mfma_f32_16x16x32_bf16 v[30:33], v[130:133], v[192:195], v[30:33]
	v_mfma_f32_16x16x32_bf16 v[14:17], v[130:133], v[196:199], v[14:17]
	v_mfma_f32_16x16x32_bf16 v[10:13], v[130:133], v[200:203], v[10:13]
	v_mfma_f32_16x16x32_bf16 v[6:9], v[130:133], v[204:207], v[6:9]
	v_mfma_f32_16x16x32_bf16 v[2:5], v[130:133], v[208:211], v[2:5]
	s_waitcnt vmcnt(0) lgkmcnt(0)
	s_barrier
	s_add_u32 s16, s16, 0x80
	s_addc_u32 s17, s17, 0
	s_add_i32 s22, s22, 0x10000
	s_add_i32 s21, s21, 1
	s_cmpk_eq_i32 s16, 0x2000
	s_cbranch_scc1 .Lmyg1279_tail
	s_add_i32 s100, s22, 0xffff0000
	s_and_b32 s100, s100, 0x10000
	v_add_u32_e32 v0, s100, v179
	v_add3_u32 v212, v0, v180, v181
	v_add3_u32 v0, v0, v182, v181
	s_cmp_gt_u32 s21, 62
	s_cbranch_scc1 .Lmyg1279_nodma
	s_bitcmp1_b32 s101, 1
	s_cbranch_scc1 .Lmyg1279_defer
	s_setprio 3
	s_and_b32 s23, s22, 0x10000
	s_add_i32 s23, s23, 0
	s_add_i32 s24, s23, 0x2000
	s_add_i32 s23, s23, 0xa000
	v_add_u32_e32 v224, s23, v140
	v_lshl_add_u64 v[222:223], v[166:167], 0, s[16:17]
	v_readfirstlane_b32 s25, v224
	v_add_u32_e32 v224, s24, v140
	s_mov_b32 m0, s25
	v_readfirstlane_b32 s25, v224
	v_add_u32_e32 v224, s23, v142
	global_load_lds_dwordx4 v[222:223], off
	v_lshl_add_u64 v[222:223], v[156:157], 0, s[16:17]
	s_mov_b32 m0, s25
	v_readfirstlane_b32 s25, v224
	v_add_u32_e32 v224, s24, v142
	global_load_lds_dwordx4 v[222:223], off
	v_lshl_add_u64 v[222:223], v[164:165], 0, s[16:17]
	s_mov_b32 m0, s25
	v_readfirstlane_b32 s25, v224
	v_add_u32_e32 v224, s23, v144
	global_load_lds_dwordx4 v[222:223], off
	v_lshl_add_u64 v[222:223], v[154:155], 0, s[16:17]
	s_mov_b32 m0, s25
	v_readfirstlane_b32 s25, v224
	v_add_u32_e32 v224, s24, v144
	global_load_lds_dwordx4 v[222:223], off
	v_lshl_add_u64 v[222:223], v[160:161], 0, s[16:17]
	s_mov_b32 m0, s25
	v_readfirstlane_b32 s25, v224
	v_add_u32_e32 v224, s23, v146
	global_load_lds_dwordx4 v[222:223], off
	v_lshl_add_u64 v[222:223], v[152:153], 0, s[16:17]
	s_mov_b32 m0, s25
	v_readfirstlane_b32 s23, v224
	v_add_u32_e32 v224, s24, v146
	global_load_lds_dwordx4 v[222:223], off
	v_lshl_add_u64 v[222:223], v[158:159], 0, s[16:17]
	s_mov_b32 m0, s23
	v_readfirstlane_b32 s23, v224
	global_load_lds_dwordx4 v[222:223], off
	v_lshl_add_u64 v[222:223], v[150:151], 0, s[16:17]
	s_mov_b32 m0, s23
	s_nop 0
	global_load_lds_dwordx4 v[222:223], off
	s_setprio 0
	s_branch .Lmyg1279_nodma
